# S1 delay of the 5-tile workgroups in L1 up-projection reduced from 4 to 3 sleeps (on FN 13,16 + PS)
# baseline (speedup 1.0000x reference)
; #define PG8_STAGE(bufoff, gbase, voff) do { _Pragma("unroll") for (int _i = 0; _i < 2; ++_i) \
;         __builtin_amdgcn_global_load_lds((const unsigned*)((const char*)(gbase) + (voff)[_i]), (LAS unsigned*)(lds + (bufoff) + ldsw + _i * 8192), 16, 0, 0); } while (0)
; #define PG8_WAIT_V(n) asm volatile("s_waitcnt vmcnt(" #n ")" ::: "memory")
; #define PG8_BAR __builtin_amdgcn_s_barrier()
; __device__ __forceinline__ bool gemm_phase(LAS unsigned char* lds, int l, int sub, int gi, bool dry = false) {
;     ...
;     Unit cur, nxt; int ui = 0;
;     if (!unit_next(g, 0, cur)) return true;
;     f32x4 acc[2][2][4][2];
; #pragma unroll
;     for (int a = 0; a < 2; ++a)
; #pragma unroll
;         for (int b = 0; b < 2; ++b)
; #pragma unroll
;             for (int m = 0; m < 4; ++m)
; #pragma unroll
;                 for (int n = 0; n < 2; ++n) acc[a][b][m][n] = (f32x4){0.f, 0.f, 0.f, 0.f};
;     bf16x8 At[4][2], B0[2][2], B1[2][2];
;     const char* cA = (const char*)g.A + (size_t)cur.pm * tstepA + (size_t)cur.k0 * kstep; const char* cB = (const char*)g.Bt + (size_t)cur.pn * tstepB + (size_t)cur.k0 * kstep;
;     PG8_STAGE(PG8_SB(0, 0), cB, voffB); PG8_STAGE(PG8_SA(0, 0), cA, voffA); PG8_STAGE(PG8_SB(0, 1), cB + hstepB, voffB); PG8_STAGE(PG8_SA(0, 1), cA + hstepA, voffA);
;     if (wr == 1) PG8_BAR;
;     PG8_WAIT_V(4); PG8_BAR;
;     PG8_STAGE(PG8_SB(1, 0), cB + kstep, voffB); PG8_STAGE(PG8_SA(1, 0), cA + kstep, voffA); PG8_STAGE(PG8_SB(1, 1), cB + hstepB + kstep, voffB);
;     PG8_WAIT_V(6); PG8_BAR;
.LBB0_243:
	s_cmp_lg_u32 s59, 0
	s_cbranch_scc1 .Lmy_nodelay
	v_readlane_b32 s4, v255, 0
	s_nop 3
	s_cmp_lg_u32 s17, 6
	s_cbranch_scc1 .Lmy_dl0
	s_cmp_lg_u32 s4, 1
	s_cbranch_scc1 .Lmy_dl0
	s_cmp_lt_u32 s26, 128
	s_cbranch_scc1 .Lmy_nodelay
	s_sleep 127
	s_sleep 127
	s_sleep 127
	s_branch .Lmy_nodelay
